# init adaLN loop batched + ffn gate/up weight conversion items issue their 8 row loads together (one wait, one 16-byte LDS write)
# speedup vs baseline: 1.0151x; 1.0049x over previous
; DI u16 bf1(float x) { return (u16)(pk2(x, 0.f) & 0xffffu); }
; DI int otid(int wv) { int lane; asm volatile("v_mbcnt_lo_u32_b32 %0, -1, 0\n\tv_mbcnt_hi_u32_b32 %0, -1, %0" : "=v"(lane)); return wv * 64 + lane; }
; DI void conv_tile(unsigned char* smem, const int wv, const float* __restrict__ src, u16* __restrict__ dst, int K, int N, int kind, const float* __restrict__ gain, int ktile, int ntile, bool kperm = false) {
;   u16(*T)[LP] = (u16(*)[LP])smem;
;   const int tid = otid(wv);
;   const int nl = tid & 63, kq = tid >> 6;
;   const int n = ntile * 64 + nl, k0 = ktile * 64;
;   __syncthreads();
; #pragma unroll 4
;   for (int i = 0; i < 8; ++i) {
;     const int k = kq * 8 + i;
;     float v = 0.f;
;     if (n < N) { v = src[(size_t)(k0 + k) * N + n]; if (gain) v *= gain[k0 + k]; }
;     T[nl][k] = bf1(v);
;   }
;   __syncthreads();
;   const int row = tid >> 3, seg = tid & 7;
;   const int nn = ntile * 64 + row;
;   if (nn < N) {
;     const int dr = perm_col(kind, nn);
;     uint4 v0;
;     if (kperm) {
;       const int base = (seg >> 2) * 32 + (seg & 1) * 16 + ((seg >> 1) & 1) * 4;
;       const uint2 lo = *(const uint2*)&T[row][base], hi = *(const uint2*)&T[row][base + 8];
;       v0 = make_uint4(lo.x, lo.y, hi.x, hi.y);
;     } else {
;       v0 = *(const uint4*)&T[row][seg * 8];
;     }
;     *(uint4*)(dst + (size_t)dr * K + k0 + seg * 8) = v0;
.LBB0_941:
	s_andn2_b64 vcc, exec, s[2:3]
	s_cbranch_vccnz .LBB0_945
	s_add_i32 s2, s19, 0xf9f8
	s_and_b32 s3, s2, 0xffff
	s_mul_i32 s3, s3, 0xba2f
	s_lshr_b32 s3, s3, 21
	s_lshl_b32 s26, s3, 6
	s_mul_i32 s3, s3, 44
	s_sub_i32 s2, s2, s3
	s_lshl_b32 s2, s2, 6
	v_mbcnt_lo_u32_b32 v0, -1, 0
	v_mbcnt_hi_u32_b32 v0, -1, v0
	s_and_b32 s27, s2, 0xffc0
	v_add_u32_e32 v1, s29, v0
	v_and_b32_e32 v183, 63, v0
	v_ashrrev_i32_e32 v2, 3, v1
	v_or_b32_e32 v100, s27, v183
	v_readlane_b32 s0, v253, 60
	v_and_b32_e32 v3, -8, v2
	v_lshlrev_b32_e32 v164, 2, v100
	v_readlane_b32 s1, v253, 61
	v_add_u32_e32 v102, s26, v3
	s_nop 0
	v_lshl_add_u64 v[100:101], s[0:1], 0, v[164:165]
	s_movk_i32 s1, 0x2c00
	v_mad_i64_i32 v[206:207], vcc, v102, s1, v[100:101]
	s_mov_b64 s[2:3], 0x2c00
	global_load_dword v212, v[206:207], off
	v_lshl_add_u64 v[208:209], v[206:207], 0, s[2:3]
	global_load_dword v213, v[208:209], off
	v_lshl_add_u64 v[206:207], v[208:209], 0, s[2:3]
	global_load_dword v214, v[206:207], off
	v_lshl_add_u64 v[208:209], v[206:207], 0, s[2:3]
	global_load_dword v215, v[208:209], off
	v_lshl_add_u64 v[206:207], v[208:209], 0, s[2:3]
	global_load_dword v216, v[206:207], off
	v_lshl_add_u64 v[208:209], v[206:207], 0, s[2:3]
	global_load_dword v217, v[208:209], off
	v_lshl_add_u64 v[206:207], v[208:209], 0, s[2:3]
	global_load_dword v218, v[206:207], off
	v_lshl_add_u64 v[208:209], v[206:207], 0, s[2:3]
	global_load_dword v219, v[208:209], off
	s_barrier
	v_lshlrev_b32_e32 v103, 1, v3
	s_movk_i32 s0, 0x90
	v_mad_u32_u24 v103, v183, s0, v103
	s_waitcnt vmcnt(0)
	v_cvt_pk_bf16_f32 v220, v212, v213
	v_cvt_pk_bf16_f32 v221, v214, v215
	v_cvt_pk_bf16_f32 v222, v216, v217
	v_cvt_pk_bf16_f32 v223, v218, v219
	ds_write_b128 v103, v[220:223]
	s_movk_i32 s0, 0xb00
	v_add_u32_e32 v3, s27, v2
	v_cmp_gt_i32_e32 vcc, s0, v3
	s_waitcnt lgkmcnt(0)
	s_barrier
	s_and_saveexec_b64 s[2:3], vcc
	s_cbranch_execz .LBB0_944
	v_lshlrev_b32_e32 v3, 1, v3
	v_and_b32_e32 v3, 0xffffffc0, v3
	v_bfe_u32 v1, v1, 3, 5
	s_movk_i32 s0, 0x90
	v_or3_b32 v100, v1, v3, 32
	v_lshlrev_b32_e32 v3, 4, v0
	v_mul_lo_u32 v1, v2, s0
	v_lshlrev_b32_e32 v2, 2, v0
	v_lshlrev_b32_e32 v0, 5, v0
	v_and_or_b32 v1, v2, 8, v1
	v_and_b32_e32 v0, 32, v0
	v_and_b32_e32 v2, 64, v3
	v_ashrrev_i32_e32 v101, 31, v100
	v_readlane_b32 s36, v251, 12
	v_add3_u32 v2, v1, v0, v2
	v_lshlrev_b64 v[0:1], 11, v[100:101]
	v_readlane_b32 s37, v251, 13
	s_mov_b32 s27, s43
	s_lshl_b32 s26, s26, 1
	v_lshl_add_u64 v[0:1], s[36:37], 0, v[0:1]
	v_lshl_add_u64 v[0:1], v[0:1], 0, s[26:27]
	v_and_b32_e32 v164, 0x70, v3
	v_lshl_add_u64 v[100:101], v[0:1], 0, v[164:165]
	ds_read2_b64 v[0:3], v2 offset1:2
	s_waitcnt lgkmcnt(0)
	global_store_dwordx4 v[100:101], v[0:3], off

; DI u16 bf1(float x) { return (u16)(pk2(x, 0.f) & 0xffffu); }
; DI int otid(int wv) { int lane; asm volatile("v_mbcnt_lo_u32_b32 %0, -1, 0\n\tv_mbcnt_hi_u32_b32 %0, -1, %0" : "=v"(lane)); return wv * 64 + lane; }
; DI void conv_tile(unsigned char* smem, const int wv, const float* __restrict__ src, u16* __restrict__ dst, int K, int N, int kind, const float* __restrict__ gain, int ktile, int ntile, bool kperm = false) {
;   u16(*T)[LP] = (u16(*)[LP])smem;
;   const int tid = otid(wv);
;   const int nl = tid & 63, kq = tid >> 6;
;   const int n = ntile * 64 + nl, k0 = ktile * 64;
;   __syncthreads();
; #pragma unroll 4
;   for (int i = 0; i < 8; ++i) {
;     const int k = kq * 8 + i;
;     float v = 0.f;
;     if (n < N) { v = src[(size_t)(k0 + k) * N + n]; if (gain) v *= gain[k0 + k]; }
;     T[nl][k] = bf1(v);
;   }
;   __syncthreads();
;   const int row = tid >> 3, seg = tid & 7;
;   const int nn = ntile * 64 + row;
;   if (nn < N) {
;     const int dr = perm_col(kind, nn);
;     uint4 v0;
;     if (kperm) {
;       const int base = (seg >> 2) * 32 + (seg & 1) * 16 + ((seg >> 1) & 1) * 4;
;       const uint2 lo = *(const uint2*)&T[row][base], hi = *(const uint2*)&T[row][base + 8];
;       v0 = make_uint4(lo.x, lo.y, hi.x, hi.y);
;     } else {
;       v0 = *(const uint4*)&T[row][seg * 8];
;     }
;     *(uint4*)(dst + (size_t)dr * K + k0 + seg * 8) = v0;
.LBB0_946:
	s_andn2_b64 vcc, exec, s[2:3]
	s_cbranch_vccnz .LBB0_950
	s_add_i32 s2, s19, 0xfcb8
	s_and_b32 s3, s2, 0xffff
	s_mul_i32 s3, s3, 0xba2f
	s_lshr_b32 s3, s3, 21
	s_lshl_b32 s26, s3, 6
	s_mul_i32 s3, s3, 44
	s_sub_i32 s2, s2, s3
	s_lshl_b32 s2, s2, 6
	v_mbcnt_lo_u32_b32 v0, -1, 0
	v_mbcnt_hi_u32_b32 v0, -1, v0
	s_and_b32 s27, s2, 0xffc0
	v_add_u32_e32 v1, s29, v0
	v_and_b32_e32 v183, 63, v0
	v_ashrrev_i32_e32 v2, 3, v1
	v_or_b32_e32 v100, s27, v183
	v_and_b32_e32 v3, -8, v2
	v_lshlrev_b32_e32 v164, 2, v100
	v_lshl_add_u64 v[100:101], s[88:89], 0, v[164:165]
	v_add_u32_e32 v102, s26, v3
	s_movk_i32 s1, 0x2c00
	v_mad_i64_i32 v[206:207], vcc, v102, s1, v[100:101]
	s_mov_b64 s[2:3], 0x2c00
	global_load_dword v212, v[206:207], off
	v_lshl_add_u64 v[208:209], v[206:207], 0, s[2:3]
	global_load_dword v213, v[208:209], off
	v_lshl_add_u64 v[206:207], v[208:209], 0, s[2:3]
	global_load_dword v214, v[206:207], off
	v_lshl_add_u64 v[208:209], v[206:207], 0, s[2:3]
	global_load_dword v215, v[208:209], off
	v_lshl_add_u64 v[206:207], v[208:209], 0, s[2:3]
	global_load_dword v216, v[206:207], off
	v_lshl_add_u64 v[208:209], v[206:207], 0, s[2:3]
	global_load_dword v217, v[208:209], off
	v_lshl_add_u64 v[206:207], v[208:209], 0, s[2:3]
	global_load_dword v218, v[206:207], off
	v_lshl_add_u64 v[208:209], v[206:207], 0, s[2:3]
	global_load_dword v219, v[208:209], off
	s_barrier
	v_lshlrev_b32_e32 v103, 1, v3
	s_movk_i32 s0, 0x90
	v_mad_u32_u24 v103, v183, s0, v103
	s_waitcnt vmcnt(0)
	v_cvt_pk_bf16_f32 v220, v212, v213
	v_cvt_pk_bf16_f32 v221, v214, v215
	v_cvt_pk_bf16_f32 v222, v216, v217
	v_cvt_pk_bf16_f32 v223, v218, v219
	ds_write_b128 v103, v[220:223]
	s_movk_i32 s0, 0xb00
	v_add_u32_e32 v3, s27, v2
	v_cmp_gt_i32_e32 vcc, s0, v3
	s_waitcnt lgkmcnt(0)
	s_barrier
	s_and_saveexec_b64 s[2:3], vcc
	s_cbranch_execz .LBB0_949
	v_lshlrev_b32_e32 v3, 1, v3
	v_bfe_u32 v1, v1, 3, 5
	s_movk_i32 s27, 0xffc0
	s_movk_i32 s0, 0x90
	v_and_or_b32 v100, v3, s27, v1
	v_lshlrev_b32_e32 v3, 4, v0
	v_mul_lo_u32 v1, v2, s0
	v_lshlrev_b32_e32 v2, 2, v0
	v_lshlrev_b32_e32 v0, 5, v0
	v_and_or_b32 v1, v2, 8, v1
	v_and_b32_e32 v0, 32, v0
	v_and_b32_e32 v2, 64, v3
	v_ashrrev_i32_e32 v101, 31, v100
	v_readlane_b32 s36, v251, 12
	v_add3_u32 v2, v1, v0, v2
	v_lshlrev_b64 v[0:1], 11, v[100:101]
	v_readlane_b32 s37, v251, 13
	s_mov_b32 s27, s43
	s_lshl_b32 s26, s26, 1
	v_lshl_add_u64 v[0:1], s[36:37], 0, v[0:1]
	v_lshl_add_u64 v[0:1], v[0:1], 0, s[26:27]
	v_and_b32_e32 v164, 0x70, v3
	v_lshl_add_u64 v[100:101], v[0:1], 0, v[164:165]
	ds_read2_b64 v[0:3], v2 offset1:2
	s_waitcnt lgkmcnt(0)
	global_store_dwordx4 v[100:101], v[0:3], off
